# grid barrier: last XCD leader releases every XCD generation flag directly (one fewer poll hop) in 13 of 16 barrier instances
# baseline (speedup 1.0000x reference)
.LBB0_291:
	s_andn2_saveexec_b64 s[4:5], s[4:5]
	s_cbranch_execz .LBB0_307
	v_mov_b32_e32 v2, s48
	v_add_co_u32_e32 v2, vcc, 0x3000, v2
	v_mov_b32_e32 v3, s49
	buffer_wbl2 sc1
	s_waitcnt vmcnt(0)
	v_addc_co_u32_e32 v3, vcc, 0, v3, vcc
	flat_atomic_add v2, v[2:3], v168 offset:1024 sc0
	v_cvt_f32_u32_e32 v3, v0
	v_sub_u32_e32 v4, 0, v0
	s_mov_b64 s[8:9], -1
	v_rcp_iflag_f32_e32 v3, v3
	s_nop 0
	v_mul_f32_e32 v3, 0x4f7ffffe, v3
	v_cvt_u32_f32_e32 v3, v3
	v_mul_lo_u32 v4, v4, v3
	v_mul_hi_u32 v4, v3, v4
	v_add_u32_e32 v3, v3, v4
	s_waitcnt vmcnt(0) lgkmcnt(0)
	v_mul_hi_u32 v3, v2, v3
	v_mul_lo_u32 v4, v3, v0
	v_sub_u32_e32 v4, v2, v4
	v_cmp_ge_u32_e32 vcc, v4, v0
	v_add_u32_e32 v5, 1, v3
	s_nop 0
	v_cndmask_b32_e32 v3, v3, v5, vcc
	v_sub_u32_e32 v5, v4, v0
	v_cndmask_b32_e32 v4, v4, v5, vcc
	v_cmp_ge_u32_e32 vcc, v4, v0
	v_add_u32_e32 v4, 1, v3
	v_add_u32_e32 v5, 1, v2
	v_cndmask_b32_e32 v4, v3, v4, vcc
	v_mad_u64_u32 v[2:3], s[4:5], v0, v4, v[0:1]
	s_add_u32 s4, s48, 0x3500
	s_addc_u32 s5, s49, 0
	s_add_i32 s26, s0, 0x900
	s_mov_b32 s27, 0
	s_lshl_b64 s[26:27], s[26:27], 2
	s_add_u32 s26, s48, s26
	s_addc_u32 s27, s49, s27
	v_cmp_ne_u32_e32 vcc, v5, v2
	v_mov_b64_e32 v[2:3], s[4:5]
	s_and_saveexec_b64 s[6:7], vcc
	s_cbranch_execz .LBB0_304
	v_mov_b64_e32 v[2:3], s[26:27]
	flat_load_dword v0, v[2:3] sc1
	s_mov_b64 s[14:15], 0
	s_waitcnt vmcnt(0) lgkmcnt(0)
	v_cmp_eq_u32_e32 vcc, v0, v4
	s_and_saveexec_b64 s[12:13], vcc
	s_cbranch_execz .LBB0_303
	s_add_u32 s8, s48, 0x200
	s_addc_u32 s9, s49, 0
	s_mov_b32 s1, 1
	s_branch .LBB0_296

.LBB0_301:
	v_mov_b64_e32 v[2:3], s[26:27]
	flat_load_dword v0, v[2:3] sc1
	s_add_i32 s1, s1, 1
	s_or_b64 s[20:21], s[20:21], exec
	s_waitcnt vmcnt(0) lgkmcnt(0)
	v_cmp_ne_u32_e32 vcc, v0, v4
	s_orn2_b64 s[18:19], vcc, exec
	s_branch .LBB0_295

.LBB0_304:
	s_or_b64 exec, exec, s[6:7]
	s_and_saveexec_b64 s[4:5], s[8:9]
	s_cbranch_execz .LBB0_306
	flat_atomic_add v[2:3], v168
	s_add_u32 s6, s48, 0x3500
	v_cmp_eq_u32_e32 vcc, s6, v2
	s_and_saveexec_b64 s[6:7], vcc
	s_cbranch_execz .Lxg_skip_12
	s_add_u32 s12, s48, 0x2400
	s_addc_u32 s13, s49, 0
	v_mov_b64_e32 v[4:5], s[12:13]
	flat_atomic_add v[4:5], v168
	flat_atomic_add v[4:5], v168 offset:256
	flat_atomic_add v[4:5], v168 offset:512
	flat_atomic_add v[4:5], v168 offset:768
	flat_atomic_add v[4:5], v168 offset:1024
	flat_atomic_add v[4:5], v168 offset:1280
	flat_atomic_add v[4:5], v168 offset:1536
	flat_atomic_add v[4:5], v168 offset:1792
	flat_atomic_add v[4:5], v168 offset:2048
	flat_atomic_add v[4:5], v168 offset:2304
	flat_atomic_add v[4:5], v168 offset:2560
	flat_atomic_add v[4:5], v168 offset:2816
	flat_atomic_add v[4:5], v168 offset:3072
	flat_atomic_add v[4:5], v168 offset:3328
	flat_atomic_add v[4:5], v168 offset:3584
	flat_atomic_add v[4:5], v168 offset:3840

.LBB0_306:
	s_or_b64 exec, exec, s[4:5]
	s_add_i32 s44, s0, 0x900
	s_lshl_b64 s[0:1], s[44:45], 2
	s_add_u32 s0, s48, s0
	s_addc_u32 s1, s49, s1
	v_mov_b64_e32 v[2:3], s[0:1]
	s_waitcnt vmcnt(0) lgkmcnt(0)
	buffer_inv sc1
	s_waitcnt vmcnt(0)

.LBB0_1052:
	s_or_b64 exec, exec, s[4:5]
	s_addk_i32 s0, 0x900
	s_mov_b32 s1, s45
	s_lshl_b64 s[0:1], s[0:1], 2
	s_add_u32 s0, s48, s0
	s_addc_u32 s1, s49, s1
	v_mov_b64_e32 v[2:3], s[0:1]
	s_waitcnt vmcnt(0) lgkmcnt(0)
	buffer_inv sc1
	s_waitcnt vmcnt(0)
